# speedup vs baseline: 1.0965x; 1.0010x over previous
.Lgo_go:
	v_lshrrev_b32_e32 v90, 3, v93
	v_and_b32_e32 v195, 7, v93
	v_bfe_u32 v232, v90, 1, 3
	v_xor_b32_e32 v195, v195, v232
	v_lshlrev_b32_e32 v195, 4, v195
	v_lshl_or_b32 v166, v90, 12, v195
	v_add_u32_e32 v167, 0x20000, v166
	v_add_u32_e32 v168, 0x40000, v166
	v_add_u32_e32 v169, 0x60000, v166
	v_and_b32_e32 v232, 12, v90
	v_lshlrev_b32_e32 v232, 1, v232
	v_and_or_b32 v232, v90, 3, v232
	v_lshrrev_b32_e32 v90, 4, v90
	v_lshl_or_b32 v232, v90, 2, v232
	v_lshl_or_b32 v170, v232, 12, v195
	v_add_u32_e32 v171, 0x20000, v170
	v_add_u32_e32 v172, 0x40000, v170
	v_add_u32_e32 v173, 0x60000, v170
	v_lshrrev_b32_e32 v90, 6, v93
	v_and_b32_e32 v195, 15, v93
	v_readfirstlane_b32 s17, v90
	v_bfe_u32 v232, v93, 4, 2
	s_lshl_b32 s14, s17, 10
	s_lshr_b32 s20, s17, 1
	s_and_b32 s21, s17, 1
	s_lshl_b32 s20, s20, 6
	s_lshl_b32 s21, s21, 6
	v_bfe_u32 v90, v195, 1, 3
	v_xor_b32_e32 v90, v90, v232
	v_lshlrev_b32_e32 v90, 4, v90
	v_add_u32_e32 v229, s20, v195
	v_add_u32_e32 v231, s21, v195
	v_lshl_or_b32 v228, v229, 7, v90
	v_lshl_or_b32 v230, v231, 7, v90
	v_xor_b32_e32 v229, 64, v228
	v_xor_b32_e32 v231, 64, v230
	v_lshrrev_b32_e32 v232, 7, v228
	v_bfe_u32 v195, v93, 4, 2
	v_lshrrev_b32_e32 v90, 6, v93
	v_and_b32_e32 v90, 1, v90
	v_lshlrev_b32_e32 v90, 6, v90
	v_lshl_add_u32 v195, v195, 3, v90
	v_lshlrev_b32_e32 v90, 2, v195
	v_lshl_add_u32 v89, v232, 13, v90
	v_add_u32_e32 v228, 0x0, v228
	v_add_u32_e32 v229, 0x0, v229
	s_and_b32 s0, s2, 7
	s_lshl_b32 s0, s0, 3
	s_bfe_u32 s1, s2, 0x30003
	s_or_b32 s23, s0, s1
	s_lshr_b32 s18, s2, 6
	s_add_u32 s19, s18, 8
	v_readlane_b32 s4, v236, 51
	v_readlane_b32 s5, v236, 52
	s_lshl_b32 s0, s23, 19
	s_add_u32 s4, s4, s0
	s_addc_u32 s5, s5, 0
	v_readlane_b32 s10, v233, 24
	v_readlane_b32 s6, v236, 57
	v_readlane_b32 s7, v236, 58
	v_readlane_b32 s11, v236, 59
	v_readlane_b32 s12, v236, 60
	s_bitcmp1_b32 s10, 0
	s_cselect_b32 s6, s11, s6
	s_cselect_b32 s7, s12, s7
	s_lshl_b32 s0, s18, 19
	s_add_u32 s6, s6, s0
	s_addc_u32 s7, s7, 0
	s_add_u32 s8, s6, 0x400000
	s_addc_u32 s9, s7, 0
	s_movk_i32 s16, 4
	s_cmpk_lt_u32 s2, 0x100
	s_addc_u32 s16, s16, 0
	s_add_i32 m0, s14, 0x0
	s_nop 0
	global_load_lds_dwordx4 v166, s[4:5]
	s_add_i32 m0, s14, 0x1000
	s_nop 0
	global_load_lds_dwordx4 v167, s[4:5]
	s_add_i32 m0, s14, 0x2000
	s_nop 0
	global_load_lds_dwordx4 v168, s[4:5]
	s_add_i32 m0, s14, 0x3000
	s_nop 0
	global_load_lds_dwordx4 v169, s[4:5]
	s_add_i32 m0, s14, 0x4000
	s_nop 0
	global_load_lds_dwordx4 v170, s[8:9]
	s_add_i32 m0, s14, 0x5000
	s_nop 0
	global_load_lds_dwordx4 v171, s[8:9]
	s_add_i32 m0, s14, 0x6000
	s_nop 0
	global_load_lds_dwordx4 v172, s[8:9]
	s_add_i32 m0, s14, 0x7000
	s_nop 0
	global_load_lds_dwordx4 v173, s[8:9]
	s_add_i32 m0, s14, 0x8000
	s_nop 0
	global_load_lds_dwordx4 v170, s[6:7]
	s_add_i32 m0, s14, 0x9000
	s_nop 0
	global_load_lds_dwordx4 v171, s[6:7]
	s_add_i32 m0, s14, 0xa000
	s_nop 0
	global_load_lds_dwordx4 v172, s[6:7]
	s_add_i32 m0, s14, 0xb000
	s_nop 0
	global_load_lds_dwordx4 v173, s[6:7]
	v_add_u32_e32 v166, 0x80, v166
	v_add_u32_e32 v167, 0x80, v167
	v_add_u32_e32 v168, 0x80, v168
	v_add_u32_e32 v169, 0x80, v169
	v_add_u32_e32 v170, 0x80, v170
	v_add_u32_e32 v171, 0x80, v171
	v_add_u32_e32 v172, 0x80, v172
	v_add_u32_e32 v173, 0x80, v173

.Lgio_entry:
	v_readlane_b32 s0, v236, 0
	s_cmpk_lg_u32 s0, 0x200
	s_cbranch_scc1 .LBB0_442
	v_lshrrev_b32_e32 v90, 3, v93
	v_and_b32_e32 v195, 7, v93
	v_bfe_u32 v232, v90, 1, 3
	v_xor_b32_e32 v195, v195, v232
	v_lshlrev_b32_e32 v195, 4, v195
	v_lshl_or_b32 v166, v90, 12, v195
	v_add_u32_e32 v167, 0x20000, v166
	v_add_u32_e32 v168, 0x40000, v166
	v_add_u32_e32 v169, 0x60000, v166
	v_and_b32_e32 v232, 12, v90
	v_lshlrev_b32_e32 v232, 1, v232
	v_and_or_b32 v232, v90, 3, v232
	v_lshrrev_b32_e32 v90, 4, v90
	v_lshl_or_b32 v232, v90, 2, v232
	v_lshl_or_b32 v170, v232, 12, v195
	v_add_u32_e32 v171, 0x20000, v170
	v_add_u32_e32 v172, 0x40000, v170
	v_add_u32_e32 v173, 0x60000, v170
	v_lshrrev_b32_e32 v90, 6, v93
	v_and_b32_e32 v195, 15, v93
	v_readfirstlane_b32 s17, v90
	v_bfe_u32 v232, v93, 4, 2
	s_lshl_b32 s14, s17, 10
	s_lshr_b32 s20, s17, 1
	s_and_b32 s21, s17, 1
	s_lshl_b32 s20, s20, 6
	s_lshl_b32 s21, s21, 6
	v_bfe_u32 v90, v195, 1, 3
	v_xor_b32_e32 v90, v90, v232
	v_lshlrev_b32_e32 v90, 4, v90
	v_add_u32_e32 v229, s20, v195
	v_add_u32_e32 v231, s21, v195
	v_lshl_or_b32 v228, v229, 7, v90
	v_lshl_or_b32 v230, v231, 7, v90
	v_lshl_add_u32 v232, v232, 3, s21
	v_lshlrev_b32_e32 v232, 1, v232
	v_lshl_or_b32 v89, v229, 14, v232
	v_xor_b32_e32 v229, 64, v228
	v_xor_b32_e32 v231, 64, v230
	v_add_u32_e32 v228, 0x0, v228
	v_add_u32_e32 v229, 0x0, v229
	s_and_b32 s0, s2, 1
	s_lshl_b32 s0, s0, 3
	s_bfe_u32 s1, s2, 0x30003
	s_or_b32 s20, s0, s1
	s_bfe_u32 s0, s2, 0x20001
	s_lshl_b32 s0, s0, 3
	s_lshr_b32 s1, s2, 6
	s_or_b32 s21, s0, s1
	v_readlane_b32 s4, v236, 51
	v_readlane_b32 s5, v236, 52
	v_readlane_b32 s6, v236, 55
	v_readlane_b32 s7, v236, 56
	v_readlane_b32 s10, v236, 53
	v_readlane_b32 s11, v236, 54
	s_lshl_b32 s0, s20, 19
	s_add_u32 s4, s4, s0
	s_addc_u32 s5, s5, 0
	s_lshl_b32 s0, s21, 19
	s_add_u32 s6, s6, s0
	s_addc_u32 s7, s7, 0
	s_add_u32 s8, s6, 0x1000000
	s_addc_u32 s9, s7, 0
	s_lshl_b32 s0, s20, 21
	s_add_u32 s10, s10, s0
	s_addc_u32 s11, s11, 0
	s_lshl_b32 s0, s21, 8
	s_add_u32 s10, s10, s0
	s_addc_u32 s11, s11, 0
	s_add_u32 s12, s10, 0x2000
	s_addc_u32 s13, s11, 0
	s_movk_i32 s16, 18
	s_add_i32 m0, s14, 0x0
	s_nop 0
	global_load_lds_dwordx4 v166, s[4:5]
	s_add_i32 m0, s14, 0x1000
	s_nop 0
	global_load_lds_dwordx4 v167, s[4:5]
	s_add_i32 m0, s14, 0x2000
	s_nop 0
	global_load_lds_dwordx4 v168, s[4:5]
	s_add_i32 m0, s14, 0x3000
	s_nop 0
	global_load_lds_dwordx4 v169, s[4:5]
	s_add_i32 m0, s14, 0x4000
	s_nop 0
	global_load_lds_dwordx4 v170, s[8:9]
	s_add_i32 m0, s14, 0x5000
	s_nop 0
	global_load_lds_dwordx4 v171, s[8:9]
	s_add_i32 m0, s14, 0x6000
	s_nop 0
	global_load_lds_dwordx4 v172, s[8:9]
	s_add_i32 m0, s14, 0x7000
	s_nop 0
	global_load_lds_dwordx4 v173, s[8:9]
	s_add_i32 m0, s14, 0x8000
	s_nop 0
	global_load_lds_dwordx4 v170, s[6:7]
	s_add_i32 m0, s14, 0x9000
	s_nop 0
	global_load_lds_dwordx4 v171, s[6:7]
	s_add_i32 m0, s14, 0xa000
	s_nop 0
	global_load_lds_dwordx4 v172, s[6:7]
	s_add_i32 m0, s14, 0xb000
	s_nop 0
	global_load_lds_dwordx4 v173, s[6:7]
	v_add_u32_e32 v166, 0x80, v166
	v_add_u32_e32 v167, 0x80, v167
	v_add_u32_e32 v168, 0x80, v168
	v_add_u32_e32 v169, 0x80, v169
	v_add_u32_e32 v170, 0x80, v170
	v_add_u32_e32 v171, 0x80, v171
	v_add_u32_e32 v172, 0x80, v172
	v_add_u32_e32 v173, 0x80, v173

.Lgie_go:
	v_lshrrev_b32_e32 v90, 3, v93
	v_and_b32_e32 v195, 7, v93
	v_bfe_u32 v232, v90, 1, 3
	v_xor_b32_e32 v195, v195, v232
	v_lshlrev_b32_e32 v195, 4, v195
	v_lshl_or_b32 v166, v90, 12, v195
	v_add_u32_e32 v167, 0x20000, v166
	v_add_u32_e32 v168, 0x40000, v166
	v_add_u32_e32 v169, 0x60000, v166
	v_and_b32_e32 v232, 12, v90
	v_lshlrev_b32_e32 v232, 1, v232
	v_and_or_b32 v232, v90, 3, v232
	v_lshrrev_b32_e32 v90, 4, v90
	v_lshl_or_b32 v232, v90, 2, v232
	v_lshl_or_b32 v170, v232, 12, v195
	v_add_u32_e32 v171, 0x20000, v170
	v_add_u32_e32 v172, 0x40000, v170
	v_add_u32_e32 v173, 0x60000, v170
	v_lshrrev_b32_e32 v90, 6, v93
	v_and_b32_e32 v195, 15, v93
	v_readfirstlane_b32 s17, v90
	v_bfe_u32 v232, v93, 4, 2
	s_lshl_b32 s14, s17, 10
	s_lshr_b32 s20, s17, 1
	s_and_b32 s21, s17, 1
	s_lshl_b32 s20, s20, 6
	s_lshl_b32 s21, s21, 6
	v_bfe_u32 v90, v195, 1, 3
	v_xor_b32_e32 v90, v90, v232
	v_lshlrev_b32_e32 v90, 4, v90
	v_add_u32_e32 v229, s20, v195
	v_add_u32_e32 v231, s21, v195
	v_lshl_or_b32 v228, v229, 7, v90
	v_lshl_or_b32 v230, v231, 7, v90
	v_xor_b32_e32 v229, 64, v228
	v_xor_b32_e32 v231, 64, v230
	v_add_u32_e32 v228, 0x0, v228
	v_add_u32_e32 v229, 0x0, v229
	s_and_b32 s0, s2, 1
	s_lshl_b32 s0, s0, 3
	s_bfe_u32 s1, s2, 0x30003
	s_or_b32 s23, s0, s1
	s_bfe_u32 s0, s2, 0x20001
	s_lshl_b32 s0, s0, 3
	s_lshr_b32 s1, s2, 6
	s_or_b32 s17, s0, s1
	s_lshl_b32 s0, s17, 1
	s_sub_u32 s1, s0, 16
	s_add_u32 s10, s0, 8
	s_add_u32 s11, s17, 32
	s_mov_b32 s18, s17
	s_mov_b32 s19, s11
	s_mov_b32 s24, 0
	s_cmp_ge_u32 s17, 8
	s_cselect_b32 s24, 1, s24
	s_cmp_ge_u32 s17, 16
	s_cselect_b32 s24, 2, s24
	s_cselect_b32 s18, s1, s18
	s_cmp_ge_u32 s17, 20
	s_cselect_b32 s24, 0, s24
	s_cselect_b32 s18, s10, s18
	s_cmp_ge_u32 s17, 24
	s_cselect_b32 s18, s17, s18
	s_add_u32 s12, s18, 1
	s_cmp_ge_u32 s17, 16
	s_cselect_b32 s19, s12, s19
	s_cmp_ge_u32 s17, 24
	s_cselect_b32 s19, s11, s19
	v_readlane_b32 s4, v236, 51
	v_readlane_b32 s5, v236, 52
	v_readlane_b32 s6, v236, 55
	v_readlane_b32 s7, v236, 56
	s_lshl_b32 s0, s23, 19
	s_add_u32 s4, s4, s0
	s_addc_u32 s5, s5, 0
	s_lshl_b32 s0, s19, 19
	s_add_u32 s8, s6, s0
	s_addc_u32 s9, s7, 0
	s_lshl_b32 s0, s18, 19
	s_add_u32 s6, s6, s0
	s_addc_u32 s7, s7, 0
	s_bfe_u32 s0, s2, 0x20001
	s_mul_i32 s1, s0, 3
	s_add_u32 s1, s1, 1
	s_lshr_b32 s1, s1, 2
	s_lshl_b32 s1, s1, 1
	s_lshr_b32 s11, s2, 3
	s_mul_i32 s11, s11, 6
	s_and_b32 s12, s2, 1
	s_add_u32 s25, s11, s1
	s_add_u32 s25, s25, s12
	s_cmp_eq_u32 s0, 2
	s_cselect_b32 s25, -1, s25
	s_cmp_ge_i32 s25, 288
	s_cselect_b32 s25, -1, s25
	s_movk_i32 s16, 18
	s_cmp_ge_i32 s25, 0
	s_addc_u32 s16, s16, 0
	s_cmp_eq_u32 s24, 2
	s_cbranch_scc1 .Lgie_lanev
	v_bfe_u32 v232, v228, 7, 7
	v_bfe_u32 v195, v93, 4, 2
	v_lshrrev_b32_e32 v90, 6, v93
	v_and_b32_e32 v90, 1, v90
	v_lshlrev_b32_e32 v90, 6, v90
	v_lshl_add_u32 v195, v195, 3, v90
	v_mul_u32_u24_e32 v89, 0x4200, v232
	v_lshl_add_u32 v89, v195, 1, v89
	v_lshlrev_b32_e32 v90, 12, v232
	v_lshl_add_u32 v90, v195, 2, v90
	s_branch .Lgie_lanedone

.Lgie_k_z:
	s_waitcnt vmcnt(0)
	s_barrier
	s_add_i32 m0, s14, 0xc000
	s_nop 0
	global_load_lds_dwordx4 v170, s[6:7]
	s_add_i32 m0, s14, 0xd000
	s_nop 0
	global_load_lds_dwordx4 v171, s[6:7]
	s_add_i32 m0, s14, 0xe000
	s_nop 0
	global_load_lds_dwordx4 v172, s[6:7]
	s_add_i32 m0, s14, 0xf000
	s_nop 0
	global_load_lds_dwordx4 v173, s[6:7]
	ds_read_b128 v[196:199], v228 offset:0
	ds_read_b128 v[200:203], v228 offset:2048
	ds_read_b128 v[204:207], v228 offset:4096
	ds_read_b128 v[208:211], v228 offset:6144
	ds_read_b128 v[212:215], v229 offset:0
	ds_read_b128 v[216:219], v229 offset:2048
	ds_read_b128 v[220:223], v229 offset:4096
	ds_read_b128 v[224:227], v229 offset:6144
	ds_read_b128 v[64:67], v230 offset:16384
	ds_read_b128 v[68:71], v230 offset:18432
	ds_read_b128 v[72:75], v230 offset:20480
	ds_read_b128 v[76:79], v230 offset:22528
	ds_read_b128 v[80:83], v231 offset:16384
	ds_read_b128 v[84:87], v231 offset:18432
	ds_read_b128 v[158:161], v231 offset:20480
	ds_read_b128 v[162:165], v231 offset:22528
	s_waitcnt lgkmcnt(0)
	s_barrier
	s_setprio 1
	s_add_i32 m0, s14, 0x0
	v_mfma_f32_16x16x32_bf16 v[94:97], v[64:67], v[196:199], v[94:97]
	global_load_lds_dwordx4 v166, s[4:5]
	v_mfma_f32_16x16x32_bf16 v[110:113], v[64:67], v[200:203], v[110:113]
	s_add_i32 m0, s14, 0x1000
	v_mfma_f32_16x16x32_bf16 v[126:129], v[64:67], v[204:207], v[126:129]
	global_load_lds_dwordx4 v167, s[4:5]
	v_mfma_f32_16x16x32_bf16 v[142:145], v[64:67], v[208:211], v[142:145]
	ds_read_b128 v[64:67], v230 offset:32768
	s_add_i32 m0, s14, 0x2000
	v_mfma_f32_16x16x32_bf16 v[98:101], v[68:71], v[196:199], v[98:101]
	global_load_lds_dwordx4 v168, s[4:5]
	v_mfma_f32_16x16x32_bf16 v[114:117], v[68:71], v[200:203], v[114:117]
	s_add_i32 m0, s14, 0x3000
	v_mfma_f32_16x16x32_bf16 v[130:133], v[68:71], v[204:207], v[130:133]
	global_load_lds_dwordx4 v169, s[4:5]
	v_mfma_f32_16x16x32_bf16 v[146:149], v[68:71], v[208:211], v[146:149]
	ds_read_b128 v[68:71], v230 offset:34816
	s_add_i32 m0, s14, 0x4000
	v_mfma_f32_16x16x32_bf16 v[102:105], v[72:75], v[196:199], v[102:105]
	global_load_lds_dwordx4 v170, s[8:9]
	v_mfma_f32_16x16x32_bf16 v[118:121], v[72:75], v[200:203], v[118:121]
	s_add_i32 m0, s14, 0x5000
	v_mfma_f32_16x16x32_bf16 v[134:137], v[72:75], v[204:207], v[134:137]
	global_load_lds_dwordx4 v171, s[8:9]
	v_mfma_f32_16x16x32_bf16 v[150:153], v[72:75], v[208:211], v[150:153]
	ds_read_b128 v[72:75], v230 offset:36864
	s_add_i32 m0, s14, 0x6000
	v_mfma_f32_16x16x32_bf16 v[106:109], v[76:79], v[196:199], v[106:109]
	global_load_lds_dwordx4 v172, s[8:9]
	v_mfma_f32_16x16x32_bf16 v[122:125], v[76:79], v[200:203], v[122:125]
	s_add_i32 m0, s14, 0x7000
	v_mfma_f32_16x16x32_bf16 v[138:141], v[76:79], v[204:207], v[138:141]
	global_load_lds_dwordx4 v173, s[8:9]
	v_mfma_f32_16x16x32_bf16 v[154:157], v[76:79], v[208:211], v[154:157]
	ds_read_b128 v[76:79], v230 offset:38912
	v_mfma_f32_16x16x32_bf16 v[94:97], v[80:83], v[212:215], v[94:97]
	v_add_u32_e32 v166, 0x80, v166
	v_mfma_f32_16x16x32_bf16 v[110:113], v[80:83], v[216:219], v[110:113]
	v_add_u32_e32 v167, 0x80, v167
	v_mfma_f32_16x16x32_bf16 v[126:129], v[80:83], v[220:223], v[126:129]
	v_add_u32_e32 v168, 0x80, v168
	v_mfma_f32_16x16x32_bf16 v[142:145], v[80:83], v[224:227], v[142:145]
	v_add_u32_e32 v169, 0x80, v169
	ds_read_b128 v[80:83], v231 offset:32768
	v_mfma_f32_16x16x32_bf16 v[98:101], v[84:87], v[212:215], v[98:101]
	v_add_u32_e32 v170, 0x80, v170
	v_mfma_f32_16x16x32_bf16 v[114:117], v[84:87], v[216:219], v[114:117]
	v_add_u32_e32 v171, 0x80, v171
	v_mfma_f32_16x16x32_bf16 v[130:133], v[84:87], v[220:223], v[130:133]
	v_add_u32_e32 v172, 0x80, v172
	v_mfma_f32_16x16x32_bf16 v[146:149], v[84:87], v[224:227], v[146:149]
	v_add_u32_e32 v173, 0x80, v173
	ds_read_b128 v[84:87], v231 offset:34816
	v_mfma_f32_16x16x32_bf16 v[102:105], v[158:161], v[212:215], v[102:105]
	v_mfma_f32_16x16x32_bf16 v[118:121], v[158:161], v[216:219], v[118:121]
	v_mfma_f32_16x16x32_bf16 v[134:137], v[158:161], v[220:223], v[134:137]
	v_mfma_f32_16x16x32_bf16 v[150:153], v[158:161], v[224:227], v[150:153]
	ds_read_b128 v[158:161], v231 offset:36864
	v_mfma_f32_16x16x32_bf16 v[106:109], v[162:165], v[212:215], v[106:109]
	v_mfma_f32_16x16x32_bf16 v[122:125], v[162:165], v[216:219], v[122:125]
	v_mfma_f32_16x16x32_bf16 v[138:141], v[162:165], v[220:223], v[138:141]
	v_mfma_f32_16x16x32_bf16 v[154:157], v[162:165], v[224:227], v[154:157]
	ds_read_b128 v[162:165], v231 offset:38912
	s_waitcnt lgkmcnt(7)
	v_mfma_f32_16x16x32_bf16 v[0:3], v[64:67], v[196:199], v[0:3]
	v_mfma_f32_16x16x32_bf16 v[16:19], v[64:67], v[200:203], v[16:19]
	v_mfma_f32_16x16x32_bf16 v[32:35], v[64:67], v[204:207], v[32:35]
	v_mfma_f32_16x16x32_bf16 v[48:51], v[64:67], v[208:211], v[48:51]
	s_waitcnt lgkmcnt(6)
	v_mfma_f32_16x16x32_bf16 v[4:7], v[68:71], v[196:199], v[4:7]
	v_mfma_f32_16x16x32_bf16 v[20:23], v[68:71], v[200:203], v[20:23]
	v_mfma_f32_16x16x32_bf16 v[36:39], v[68:71], v[204:207], v[36:39]
	v_mfma_f32_16x16x32_bf16 v[52:55], v[68:71], v[208:211], v[52:55]
	s_waitcnt lgkmcnt(5)
	v_mfma_f32_16x16x32_bf16 v[8:11], v[72:75], v[196:199], v[8:11]
	v_mfma_f32_16x16x32_bf16 v[24:27], v[72:75], v[200:203], v[24:27]
	v_mfma_f32_16x16x32_bf16 v[40:43], v[72:75], v[204:207], v[40:43]
	v_mfma_f32_16x16x32_bf16 v[56:59], v[72:75], v[208:211], v[56:59]
	s_waitcnt lgkmcnt(4)
	v_mfma_f32_16x16x32_bf16 v[12:15], v[76:79], v[196:199], v[12:15]
	v_mfma_f32_16x16x32_bf16 v[28:31], v[76:79], v[200:203], v[28:31]
	v_mfma_f32_16x16x32_bf16 v[44:47], v[76:79], v[204:207], v[44:47]
	v_mfma_f32_16x16x32_bf16 v[60:63], v[76:79], v[208:211], v[60:63]
	s_waitcnt lgkmcnt(3)
	v_mfma_f32_16x16x32_bf16 v[0:3], v[80:83], v[212:215], v[0:3]
	v_mfma_f32_16x16x32_bf16 v[16:19], v[80:83], v[216:219], v[16:19]
	v_mfma_f32_16x16x32_bf16 v[32:35], v[80:83], v[220:223], v[32:35]
	v_mfma_f32_16x16x32_bf16 v[48:51], v[80:83], v[224:227], v[48:51]
	s_waitcnt lgkmcnt(2)
	v_mfma_f32_16x16x32_bf16 v[4:7], v[84:87], v[212:215], v[4:7]
	v_mfma_f32_16x16x32_bf16 v[20:23], v[84:87], v[216:219], v[20:23]
	v_mfma_f32_16x16x32_bf16 v[36:39], v[84:87], v[220:223], v[36:39]
	v_mfma_f32_16x16x32_bf16 v[52:55], v[84:87], v[224:227], v[52:55]
	s_waitcnt lgkmcnt(1)
	v_mfma_f32_16x16x32_bf16 v[8:11], v[158:161], v[212:215], v[8:11]
	v_mfma_f32_16x16x32_bf16 v[24:27], v[158:161], v[216:219], v[24:27]
	v_mfma_f32_16x16x32_bf16 v[40:43], v[158:161], v[220:223], v[40:43]
	v_mfma_f32_16x16x32_bf16 v[56:59], v[158:161], v[224:227], v[56:59]
	s_waitcnt lgkmcnt(0)
	v_mfma_f32_16x16x32_bf16 v[12:15], v[162:165], v[212:215], v[12:15]
	v_mfma_f32_16x16x32_bf16 v[28:31], v[162:165], v[216:219], v[28:31]
	v_mfma_f32_16x16x32_bf16 v[44:47], v[162:165], v[220:223], v[44:47]
	v_mfma_f32_16x16x32_bf16 v[60:63], v[162:165], v[224:227], v[60:63]
	s_setprio 0
	s_waitcnt vmcnt(0)
	s_barrier
	ds_read_b128 v[196:199], v228 offset:0
	ds_read_b128 v[200:203], v228 offset:2048
	ds_read_b128 v[204:207], v228 offset:4096
	ds_read_b128 v[208:211], v228 offset:6144
	ds_read_b128 v[212:215], v229 offset:0
	ds_read_b128 v[216:219], v229 offset:2048
	ds_read_b128 v[220:223], v229 offset:4096
	ds_read_b128 v[224:227], v229 offset:6144
	ds_read_b128 v[64:67], v230 offset:16384
	ds_read_b128 v[68:71], v230 offset:18432
	ds_read_b128 v[72:75], v230 offset:20480
	ds_read_b128 v[76:79], v230 offset:22528
	ds_read_b128 v[80:83], v231 offset:16384
	ds_read_b128 v[84:87], v231 offset:18432
	ds_read_b128 v[158:161], v231 offset:20480
	ds_read_b128 v[162:165], v231 offset:22528
	s_cmp_lg_u32 s15, 1
	s_cbranch_scc1 .Lhk_done_z
	s_add_u32 s4, s4, 0xfffff000
	s_addc_u32 s5, s5, -1
	s_add_u32 s6, s6, 0xfffff000
	s_addc_u32 s7, s7, -1
	s_add_u32 s8, s8, 0xfffff000
	s_addc_u32 s9, s9, -1
	s_cmp_eq_u32 s16, 1
	s_cbranch_scc1 .Lhk_done_z
	s_cmp_eq_u32 s16, 2
	s_cbranch_scc0 .Lhk_reg_z
	s_cmp_ge_i32 s25, 0
	s_cbranch_scc0 .Lhk_reg_z
	v_readlane_b32 s0, v236, 51
	v_readlane_b32 s1, v236, 52
	s_lshl_b32 s10, s25, 19
	s_add_u32 s4, s0, s10
	s_addc_u32 s5, s1, 0
	s_sub_u32 s4, s4, 0x12000
	s_subb_u32 s5, s5, 0
	v_readlane_b32 s0, v236, 55
	v_readlane_b32 s1, v236, 56
	s_add_u32 s6, s0, 0x1fee000
	s_addc_u32 s7, s1, 0
	s_add_u32 s8, s0, 0x206e000
	s_addc_u32 s9, s1, 0
	s_branch .Lhk_done_z

.Lgie_k_v:
	s_waitcnt vmcnt(0)
	s_barrier
	s_add_i32 m0, s14, 0xc000
	s_nop 0
	global_load_lds_dwordx4 v170, s[6:7]
	s_add_i32 m0, s14, 0xd000
	s_nop 0
	global_load_lds_dwordx4 v171, s[6:7]
	s_add_i32 m0, s14, 0xe000
	s_nop 0
	global_load_lds_dwordx4 v172, s[6:7]
	s_add_i32 m0, s14, 0xf000
	s_nop 0
	global_load_lds_dwordx4 v173, s[6:7]
	ds_read_b128 v[196:199], v228 offset:0
	ds_read_b128 v[200:203], v228 offset:2048
	ds_read_b128 v[204:207], v228 offset:4096
	ds_read_b128 v[208:211], v228 offset:6144
	ds_read_b128 v[212:215], v229 offset:0
	ds_read_b128 v[216:219], v229 offset:2048
	ds_read_b128 v[220:223], v229 offset:4096
	ds_read_b128 v[224:227], v229 offset:6144
	ds_read_b128 v[64:67], v230 offset:16384
	ds_read_b128 v[68:71], v230 offset:18432
	ds_read_b128 v[72:75], v230 offset:20480
	ds_read_b128 v[76:79], v230 offset:22528
	ds_read_b128 v[80:83], v231 offset:16384
	ds_read_b128 v[84:87], v231 offset:18432
	ds_read_b128 v[158:161], v231 offset:20480
	ds_read_b128 v[162:165], v231 offset:22528
	s_waitcnt lgkmcnt(0)
	s_barrier
	s_setprio 1
	s_add_i32 m0, s14, 0x0
	v_mfma_f32_16x16x32_bf16 v[94:97], v[196:199], v[64:67], v[94:97]
	global_load_lds_dwordx4 v166, s[4:5]
	v_mfma_f32_16x16x32_bf16 v[110:113], v[200:203], v[64:67], v[110:113]
	s_add_i32 m0, s14, 0x1000
	v_mfma_f32_16x16x32_bf16 v[126:129], v[204:207], v[64:67], v[126:129]
	global_load_lds_dwordx4 v167, s[4:5]
	v_mfma_f32_16x16x32_bf16 v[142:145], v[208:211], v[64:67], v[142:145]
	ds_read_b128 v[64:67], v230 offset:32768
	s_add_i32 m0, s14, 0x2000
	v_mfma_f32_16x16x32_bf16 v[98:101], v[196:199], v[68:71], v[98:101]
	global_load_lds_dwordx4 v168, s[4:5]
	v_mfma_f32_16x16x32_bf16 v[114:117], v[200:203], v[68:71], v[114:117]
	s_add_i32 m0, s14, 0x3000
	v_mfma_f32_16x16x32_bf16 v[130:133], v[204:207], v[68:71], v[130:133]
	global_load_lds_dwordx4 v169, s[4:5]
	v_mfma_f32_16x16x32_bf16 v[146:149], v[208:211], v[68:71], v[146:149]
	ds_read_b128 v[68:71], v230 offset:34816
	s_add_i32 m0, s14, 0x4000
	v_mfma_f32_16x16x32_bf16 v[102:105], v[196:199], v[72:75], v[102:105]
	global_load_lds_dwordx4 v170, s[8:9]
	v_mfma_f32_16x16x32_bf16 v[118:121], v[200:203], v[72:75], v[118:121]
	s_add_i32 m0, s14, 0x5000
	v_mfma_f32_16x16x32_bf16 v[134:137], v[204:207], v[72:75], v[134:137]
	global_load_lds_dwordx4 v171, s[8:9]
	v_mfma_f32_16x16x32_bf16 v[150:153], v[208:211], v[72:75], v[150:153]
	ds_read_b128 v[72:75], v230 offset:36864
	s_add_i32 m0, s14, 0x6000
	v_mfma_f32_16x16x32_bf16 v[106:109], v[196:199], v[76:79], v[106:109]
	global_load_lds_dwordx4 v172, s[8:9]
	v_mfma_f32_16x16x32_bf16 v[122:125], v[200:203], v[76:79], v[122:125]
	s_add_i32 m0, s14, 0x7000
	v_mfma_f32_16x16x32_bf16 v[138:141], v[204:207], v[76:79], v[138:141]
	global_load_lds_dwordx4 v173, s[8:9]
	v_mfma_f32_16x16x32_bf16 v[154:157], v[208:211], v[76:79], v[154:157]
	ds_read_b128 v[76:79], v230 offset:38912
	v_mfma_f32_16x16x32_bf16 v[94:97], v[212:215], v[80:83], v[94:97]
	v_add_u32_e32 v166, 0x80, v166
	v_mfma_f32_16x16x32_bf16 v[110:113], v[216:219], v[80:83], v[110:113]
	v_add_u32_e32 v167, 0x80, v167
	v_mfma_f32_16x16x32_bf16 v[126:129], v[220:223], v[80:83], v[126:129]
	v_add_u32_e32 v168, 0x80, v168
	v_mfma_f32_16x16x32_bf16 v[142:145], v[224:227], v[80:83], v[142:145]
	v_add_u32_e32 v169, 0x80, v169
	ds_read_b128 v[80:83], v231 offset:32768
	v_mfma_f32_16x16x32_bf16 v[98:101], v[212:215], v[84:87], v[98:101]
	v_add_u32_e32 v170, 0x80, v170
	v_mfma_f32_16x16x32_bf16 v[114:117], v[216:219], v[84:87], v[114:117]
	v_add_u32_e32 v171, 0x80, v171
	v_mfma_f32_16x16x32_bf16 v[130:133], v[220:223], v[84:87], v[130:133]
	v_add_u32_e32 v172, 0x80, v172
	v_mfma_f32_16x16x32_bf16 v[146:149], v[224:227], v[84:87], v[146:149]
	v_add_u32_e32 v173, 0x80, v173
	ds_read_b128 v[84:87], v231 offset:34816
	v_mfma_f32_16x16x32_bf16 v[102:105], v[212:215], v[158:161], v[102:105]
	v_mfma_f32_16x16x32_bf16 v[118:121], v[216:219], v[158:161], v[118:121]
	v_mfma_f32_16x16x32_bf16 v[134:137], v[220:223], v[158:161], v[134:137]
	v_mfma_f32_16x16x32_bf16 v[150:153], v[224:227], v[158:161], v[150:153]
	ds_read_b128 v[158:161], v231 offset:36864
	v_mfma_f32_16x16x32_bf16 v[106:109], v[212:215], v[162:165], v[106:109]
	v_mfma_f32_16x16x32_bf16 v[122:125], v[216:219], v[162:165], v[122:125]
	v_mfma_f32_16x16x32_bf16 v[138:141], v[220:223], v[162:165], v[138:141]
	v_mfma_f32_16x16x32_bf16 v[154:157], v[224:227], v[162:165], v[154:157]
	ds_read_b128 v[162:165], v231 offset:38912
	s_waitcnt lgkmcnt(7)
	v_mfma_f32_16x16x32_bf16 v[0:3], v[196:199], v[64:67], v[0:3]
	v_mfma_f32_16x16x32_bf16 v[16:19], v[200:203], v[64:67], v[16:19]
	v_mfma_f32_16x16x32_bf16 v[32:35], v[204:207], v[64:67], v[32:35]
	v_mfma_f32_16x16x32_bf16 v[48:51], v[208:211], v[64:67], v[48:51]
	s_waitcnt lgkmcnt(6)
	v_mfma_f32_16x16x32_bf16 v[4:7], v[196:199], v[68:71], v[4:7]
	v_mfma_f32_16x16x32_bf16 v[20:23], v[200:203], v[68:71], v[20:23]
	v_mfma_f32_16x16x32_bf16 v[36:39], v[204:207], v[68:71], v[36:39]
	v_mfma_f32_16x16x32_bf16 v[52:55], v[208:211], v[68:71], v[52:55]
	s_waitcnt lgkmcnt(5)
	v_mfma_f32_16x16x32_bf16 v[8:11], v[196:199], v[72:75], v[8:11]
	v_mfma_f32_16x16x32_bf16 v[24:27], v[200:203], v[72:75], v[24:27]
	v_mfma_f32_16x16x32_bf16 v[40:43], v[204:207], v[72:75], v[40:43]
	v_mfma_f32_16x16x32_bf16 v[56:59], v[208:211], v[72:75], v[56:59]
	s_waitcnt lgkmcnt(4)
	v_mfma_f32_16x16x32_bf16 v[12:15], v[196:199], v[76:79], v[12:15]
	v_mfma_f32_16x16x32_bf16 v[28:31], v[200:203], v[76:79], v[28:31]
	v_mfma_f32_16x16x32_bf16 v[44:47], v[204:207], v[76:79], v[44:47]
	v_mfma_f32_16x16x32_bf16 v[60:63], v[208:211], v[76:79], v[60:63]
	s_waitcnt lgkmcnt(3)
	v_mfma_f32_16x16x32_bf16 v[0:3], v[212:215], v[80:83], v[0:3]
	v_mfma_f32_16x16x32_bf16 v[16:19], v[216:219], v[80:83], v[16:19]
	v_mfma_f32_16x16x32_bf16 v[32:35], v[220:223], v[80:83], v[32:35]
	v_mfma_f32_16x16x32_bf16 v[48:51], v[224:227], v[80:83], v[48:51]
	s_waitcnt lgkmcnt(2)
	v_mfma_f32_16x16x32_bf16 v[4:7], v[212:215], v[84:87], v[4:7]
	v_mfma_f32_16x16x32_bf16 v[20:23], v[216:219], v[84:87], v[20:23]
	v_mfma_f32_16x16x32_bf16 v[36:39], v[220:223], v[84:87], v[36:39]
	v_mfma_f32_16x16x32_bf16 v[52:55], v[224:227], v[84:87], v[52:55]
	s_waitcnt lgkmcnt(1)
	v_mfma_f32_16x16x32_bf16 v[8:11], v[212:215], v[158:161], v[8:11]
	v_mfma_f32_16x16x32_bf16 v[24:27], v[216:219], v[158:161], v[24:27]
	v_mfma_f32_16x16x32_bf16 v[40:43], v[220:223], v[158:161], v[40:43]
	v_mfma_f32_16x16x32_bf16 v[56:59], v[224:227], v[158:161], v[56:59]
	s_waitcnt lgkmcnt(0)
	v_mfma_f32_16x16x32_bf16 v[12:15], v[212:215], v[162:165], v[12:15]
	v_mfma_f32_16x16x32_bf16 v[28:31], v[216:219], v[162:165], v[28:31]
	v_mfma_f32_16x16x32_bf16 v[44:47], v[220:223], v[162:165], v[44:47]
	v_mfma_f32_16x16x32_bf16 v[60:63], v[224:227], v[162:165], v[60:63]
	s_setprio 0
	s_waitcnt vmcnt(0)
	s_barrier
	ds_read_b128 v[196:199], v228 offset:0
	ds_read_b128 v[200:203], v228 offset:2048
	ds_read_b128 v[204:207], v228 offset:4096
	ds_read_b128 v[208:211], v228 offset:6144
	ds_read_b128 v[212:215], v229 offset:0
	ds_read_b128 v[216:219], v229 offset:2048
	ds_read_b128 v[220:223], v229 offset:4096
	ds_read_b128 v[224:227], v229 offset:6144
	ds_read_b128 v[64:67], v230 offset:16384
	ds_read_b128 v[68:71], v230 offset:18432
	ds_read_b128 v[72:75], v230 offset:20480
	ds_read_b128 v[76:79], v230 offset:22528
	ds_read_b128 v[80:83], v231 offset:16384
	ds_read_b128 v[84:87], v231 offset:18432
	ds_read_b128 v[158:161], v231 offset:20480
	ds_read_b128 v[162:165], v231 offset:22528
	s_cmp_lg_u32 s15, 1
	s_cbranch_scc1 .Lhk_done_v
	s_add_u32 s4, s4, 0xfffff000
	s_addc_u32 s5, s5, -1
	s_add_u32 s6, s6, 0xfffff000
	s_addc_u32 s7, s7, -1
	s_add_u32 s8, s8, 0xfffff000
	s_addc_u32 s9, s9, -1
	s_cmp_eq_u32 s16, 1
	s_cbranch_scc1 .Lhk_done_v
	s_cmp_eq_u32 s16, 2
	s_cbranch_scc0 .Lhk_reg_v
	s_cmp_ge_i32 s25, 0
	s_cbranch_scc0 .Lhk_reg_v
	v_readlane_b32 s0, v236, 51
	v_readlane_b32 s1, v236, 52
	s_lshl_b32 s10, s25, 19
	s_add_u32 s4, s0, s10
	s_addc_u32 s5, s1, 0
	s_sub_u32 s4, s4, 0x12000
	s_subb_u32 s5, s5, 0
	v_readlane_b32 s0, v236, 55
	v_readlane_b32 s1, v236, 56
	s_add_u32 s6, s0, 0x1fee000
	s_addc_u32 s7, s1, 0
	s_add_u32 s8, s0, 0x206e000
	s_addc_u32 s9, s1, 0
	s_branch .Lhk_done_v

.Lv_done_b:
.Lgie_next:
	s_add_u32 s23, s23, 16
	s_add_i32 s16, s16, -1
	s_cmp_eq_u32 s16, 0
	s_cbranch_scc1 .Lgie_exit
	s_cmp_eq_u32 s16, 1
	s_cbranch_scc0 .Lgie_iter
	s_cmp_ge_i32 s25, 0
	s_cbranch_scc0 .Lgie_iter
	s_mov_b32 s23, s25
	s_movk_i32 s18, 64
	s_movk_i32 s19, 65
	s_cmp_eq_u32 s24, 2
	s_mov_b32 s24, 0
	s_cbranch_scc0 .Lgie_iter
	v_bfe_u32 v232, v228, 7, 7
	v_bfe_u32 v195, v93, 4, 2
	v_lshrrev_b32_e32 v90, 6, v93
	v_and_b32_e32 v90, 1, v90
	v_lshlrev_b32_e32 v90, 6, v90
	v_lshl_add_u32 v195, v195, 3, v90
	v_mul_u32_u24_e32 v89, 0x4200, v232
	v_lshl_add_u32 v89, v195, 1, v89
	v_lshlrev_b32_e32 v90, 12, v232
	v_lshl_add_u32 v90, v195, 2, v90
	s_branch .Lgie_iter
